# phase-0 load balance: the 128 second-round modulation GEMV items moved from workgroups 0-127 (which also carry the most weight-conversion tiles) to workgroups 128-255
# speedup vs baseline: 1.0005x; 1.0005x over previous
.LBB0_1104:
	s_or_b64 exec, exec, s[0:1]
	s_cmpk_eq_i32 s88, 0x100
	s_cbranch_scc0 .Lmod_gen
	s_add_i32 s4, s4, 0x80
	s_sub_i32 s0, s4, 0x100
	s_cmp_lt_u32 s0, 0x80
	s_barrier
	s_cbranch_scc0 .LBB0_1109
	s_branch .LBB0_1105
.Lmod_gen:
	s_add_i32 s4, s4, s88
	s_cmpk_lt_i32 s4, 0x180
	s_barrier
	s_cbranch_scc0 .LBB0_1109
